# attention tile loops: waves 4-7 delayed by s_sleep 10 at the top of every tile iteration (stagger of the two waves per SIMD); on top of v026
# baseline (speedup 1.0000x reference)
; #define SEL_INIT(j_) ((MODE == 1) ? ((((smask >> (j_)) & 1u) != 0u) ? 0.f : -__builtin_inff()) : 0.f)
; template <int MODE>
; __device__ __forceinline__ void attn_branch(Frame& F, const bf16_t* Kp, const bf16_t* Vp, int j_lo, int j_hi, int sb, const bf16x8* qr, unsigned smask, f32x16* o, float& l_out) {
;     ...
;     for (int t = 0; t < NT; ++t) {
;         const int j = j_lo + t;
;         f32x16 C0, C1;
;         qkt(C0, C1, lds + AT_K + (t & 1) * SHM_T, r32, hi, qr, SEL_INIT(j));
.Lmy_ldskip_0:
	v_readfirstlane_b32 s98, v0
	s_nop 3
	s_bitcmp1_b32 s98, 8
	s_cbranch_scc0 .Lmy_nosleep_0
	s_sleep 10
